# deferred weight transposes split into four ranges balanced over the two idle slots
# speedup vs baseline: 1.0000x; 1.0000x over previous
; __global__ void __launch_bounds__(512, 2) fox_fwd(Args args) {
;     ...
;             if (r < I_O) { const int nblk = DM / 32, kb = r / nblk, nb = r % nblk;
;                 if (kb < 16) transpose_item(A_->in[15] + 32 * nb, DM, Wo, DM, 32 * nb, 64 * kb, scr, lane);
;                 else transpose_item(A_->in[15] + (size_t)FOXW * DM + 32 * nb, DM, (bf16_t*)(ws + WS_D), FOXW, 32 * nb, 64 * kb - FOXW, scr, lane);
;                 continue; }
.Lp0_m4:
	s_cmp_eq_u32 s99, 4
	s_cbranch_scc0 .Lp0_m2
	s_add_u32 s50, s16, 0x9140
	s_movk_i32 s18, 0x540
	s_mov_b32 s100, 0x9bff
	s_branch .Lp0_strides

; __global__ void __launch_bounds__(512, 2) fox_fwd(Args args) {
;     ...
;             if (r < I_INA) { const int nblk = 3 * FOXW / 32, kb = r / nblk, nb = r % nblk; transpose_item(A_->in[11] + 32 * nb, INW, Win, DM, 32 * nb, 64 * kb, scr, lane, A_->in[10]); continue; }
;             r -= I_INA;
;             if (r < I_INP) { const int nblk = POOLW / 32, kb = r / nblk, nb = r % nblk; transpose_item(A_->in[11] + 3 * FOXW + NH + 32 * nb, INW, Win, DM, 3 * FOXW + 32 * nb, 64 * kb, scr, lane, A_->in[10]); continue; }
.Lp0_m3:
	s_add_u32 s50, s16, 0x8200
	s_mov_b32 s100, 0x93ff

; __device__ __forceinline__ unsigned f2bf(float f) { unsigned u = __builtin_bit_cast(unsigned, f); return (u + 0x7fffu + ((u >> 16) & 1u)) >> 16; }
; __global__ void __launch_bounds__(512, 2) fox_fwd(Args args) {
;     ...
;         for (int i = bx * 512 + tid; i < NH * DM; i += G * 512) { const int j = i / DM, k = i % DM; Win[(size_t)(4 * FOXW + j) * DM + k] = (bf16_t)f2bf(A_->in[11][(size_t)k * INW + 3 * FOXW + j] * A_->in[10][k]); }
.LBB0_96:
	s_cmp_eq_u32 s99, 1
	s_cbranch_scc1 .Lp0_ret1
	s_cmp_eq_u32 s99, 2
	s_cbranch_scc1 .Lp0_ret2
	s_cmp_eq_u32 s99, 3
	s_cbranch_scc1 .Lp0_ret3
	s_cmp_eq_u32 s99, 4
	s_cbranch_scc1 .Lp0_ret4
	v_lshl_add_u32 v4, s2, 9, v33
	s_movk_i32 s1, 0x4000
	v_cmp_gt_i32_e32 vcc, s1, v4
	s_and_saveexec_b64 s[26:27], vcc
	s_cbranch_execz .LBB0_104
	s_lshl_b32 s0, s48, 9
	v_cvt_f32_u32_e32 v0, s0
	v_add_u32_e32 v5, s0, v4
	v_mov_b32_e32 v1, s0
	v_cmp_gt_i32_e32 vcc, s1, v5
	v_rcp_iflag_f32_e32 v0, v0
	s_sub_i32 s3, 0, s0
	v_max_i32_e32 v2, 0x4000, v5
	v_addc_co_u32_e64 v1, s[4:5], v4, v1, vcc
	v_mul_f32_e32 v0, 0x4f7ffffe, v0
	v_cvt_u32_f32_e32 v0, v0
	v_sub_u32_e32 v1, v2, v1
	s_load_dwordx4 s[12:15], s[22:23], 0x50
	s_mov_b64 s[28:29], -1
	v_mul_lo_u32 v2, s3, v0
	v_mul_hi_u32 v2, v0, v2
	v_add_u32_e32 v0, v0, v2
	v_mul_hi_u32 v0, v1, v0
	v_mul_lo_u32 v2, v0, s0
	v_sub_u32_e32 v1, v1, v2
	v_add_u32_e32 v2, 1, v0
	v_cmp_le_u32_e64 s[4:5], s0, v1
	s_nop 1
	v_cndmask_b32_e64 v0, v0, v2, s[4:5]
	v_subrev_u32_e32 v2, s0, v1
	v_cndmask_b32_e64 v1, v1, v2, s[4:5]
	v_add_u32_e32 v2, 1, v0
	v_cmp_le_u32_e64 s[4:5], s0, v1
	s_nop 1
	v_cndmask_b32_e64 v0, v0, v2, s[4:5]
	v_addc_co_u32_e32 v6, vcc, 1, v0, vcc
	v_cmp_lt_u32_e32 vcc, 1, v6
	v_mov_b32_e32 v0, v4
	s_and_saveexec_b64 s[4:5], vcc
	s_cbranch_execz .LBB0_101
	v_and_b32_e32 v7, -2, v6
	s_lshl_b32 s1, s48, 10
	s_mov_b32 s3, s1
	s_mov_b64 s[28:29], 0
	s_movk_i32 s17, 0x4020
	s_waitcnt lgkmcnt(0)
	v_mov_b64_e32 v[0:1], s[14:15]
	s_movk_i32 s19, 0x3000
	s_movk_i32 s30, 0x7fff
	s_mov_b32 s31, 0x1000000
	v_mov_b32_e32 v8, 1
	v_mov_b32_e32 v9, v7
	v_mov_b64_e32 v[2:3], v[4:5]

; #define SEAM(k) do { if (IN(k) && IN((k) + 1)) { unsigned* bar_ = (unsigned*)kargs()->ws; xcd_barrier(bar_, (volatile LAS unsigned*)((PG8_LAS unsigned char*)lds + LDS_BARST)); } } while (0)
; __global__ void __launch_bounds__(512, 2) fox_fwd(Args args) {
;     ...
;     if (IN(1)) { PTRS TIDS pg8::Gemm g{ABUF, Wgu1, MTOT, 2 * DFF, DM, DM, 0}; pg8::StaticOrder S; S.init(MTOT, 2 * DFF, DM, G, bx, 0, nullptr, nullptr);
;         pg8::EpiGU E{HB, nullptr}; pg8::gemm_phase(lds3, g, S, E); }
;     SEAM(1);
.Lp0_ret1:
	v_readlane_b32 s54, v250, 3
	v_readlane_b32 s55, v250, 4
	s_mov_b32 s99, 4
	s_nop 3
	s_branch .Lp0_reenter
